# prologue weight-transpose loops: loop-head vmcnt waits removed so the next item's loads are issued while the current item's loads are in flight
# speedup vs baseline: 1.0023x; 1.0004x over previous
.LBB0_98:
	v_add_u32_e32 v174, s51, v173
	v_cmp_gt_i32_e32 vcc, s42, v174
	s_and_saveexec_b64 s[34:35], vcc
	s_cbranch_execz .LBB0_100
	v_mul_hi_i32 v32, v174, s43
	v_lshrrev_b32_e32 v33, 31, v32
	v_ashrrev_i32_e32 v32, 5, v32
	v_add_u32_e32 v32, v32, v33
	v_lshl_or_b32 v60, v32, 6, v159
	v_mul_lo_u32 v32, v32, s44
	v_sub_u32_e32 v32, v174, v32
	v_lshlrev_b32_e32 v32, 5, v32
	v_ashrrev_i32_e32 v33, 31, v32
	v_lshl_add_u64 v[56:57], v[32:33], 2, v[154:155]
	v_mad_i64_i32 v[32:33], s[36:37], v60, s45, v[56:57]
	v_or_b32_e32 v34, 8, v60
	v_or_b32_e32 v40, 16, v60
	v_or_b32_e32 v42, 24, v60
	v_or_b32_e32 v48, 32, v60
	v_or_b32_e32 v50, 40, v60
	v_or_b32_e32 v58, 48, v60
	v_or_b32_e32 v60, 56, v60
	v_mad_i64_i32 v[34:35], s[36:37], v34, s45, v[56:57]
	v_mad_i64_i32 v[40:41], s[36:37], v40, s45, v[56:57]
	v_mad_i64_i32 v[42:43], s[36:37], v42, s45, v[56:57]
	v_mad_i64_i32 v[48:49], s[36:37], v48, s45, v[56:57]
	v_mad_i64_i32 v[50:51], s[36:37], v50, s45, v[56:57]
	v_mad_i64_i32 v[58:59], s[36:37], v58, s45, v[56:57]
	v_mad_i64_i32 v[56:57], s[36:37], v60, s45, v[56:57]
	global_load_dwordx4 v[36:39], v[32:33], off
	s_nop 0
	global_load_dwordx4 v[32:35], v[34:35], off
	s_nop 0
	global_load_dwordx4 v[44:47], v[40:41], off
	s_nop 0
	global_load_dwordx4 v[40:43], v[42:43], off
	s_nop 0
	global_load_dwordx4 v[52:55], v[48:49], off
	s_nop 0
	global_load_dwordx4 v[48:51], v[50:51], off
	s_nop 0
	global_load_dwordx4 v[60:63], v[58:59], off
	s_nop 0
	global_load_dwordx4 v[56:59], v[56:57], off

.LBB0_113:
	v_add_u32_e32 v173, s41, v174
	v_cmp_gt_i32_e32 vcc, s46, v173
	s_and_saveexec_b64 s[34:35], vcc
	s_cbranch_execz .LBB0_115
	v_ashrrev_i32_e32 v32, 31, v173
	v_lshrrev_b32_e32 v32, 25, v32
	v_add_u32_e32 v32, v173, v32
	v_ashrrev_i32_e32 v33, 7, v32
	v_and_b32_e32 v32, 0x7ffff80, v32
	v_sub_u32_e32 v32, v173, v32
	v_lshl_or_b32 v56, v33, 6, v159
	v_lshlrev_b32_e32 v32, 5, v32
	v_ashrrev_i32_e32 v33, 31, v32
	v_ashrrev_i32_e32 v57, 31, v56
	v_lshl_add_u64 v[58:59], v[32:33], 2, v[154:155]
	v_lshlrev_b64 v[32:33], 14, v[56:57]
	v_or_b32_e32 v34, 8, v56
	v_or_b32_e32 v40, 16, v56
	v_or_b32_e32 v42, 24, v56
	v_or_b32_e32 v48, 32, v56
	v_or_b32_e32 v50, 40, v56
	v_or_b32_e32 v60, 48, v56
	v_or_b32_e32 v56, 56, v56
	v_ashrrev_i32_e32 v35, 31, v34
	v_ashrrev_i32_e32 v41, 31, v40
	v_ashrrev_i32_e32 v43, 31, v42
	v_ashrrev_i32_e32 v49, 31, v48
	v_ashrrev_i32_e32 v51, 31, v50
	v_ashrrev_i32_e32 v61, 31, v60
	v_ashrrev_i32_e32 v57, 31, v56
	v_lshlrev_b64 v[34:35], 14, v[34:35]
	v_lshlrev_b64 v[40:41], 14, v[40:41]
	v_lshlrev_b64 v[42:43], 14, v[42:43]
	v_lshlrev_b64 v[48:49], 14, v[48:49]
	v_lshlrev_b64 v[50:51], 14, v[50:51]
	v_lshlrev_b64 v[60:61], 14, v[60:61]
	v_lshlrev_b64 v[56:57], 14, v[56:57]
	v_lshl_add_u64 v[32:33], v[58:59], 0, v[32:33]
	v_lshl_add_u64 v[34:35], v[58:59], 0, v[34:35]
	v_lshl_add_u64 v[40:41], v[58:59], 0, v[40:41]
	v_lshl_add_u64 v[42:43], v[58:59], 0, v[42:43]
	v_lshl_add_u64 v[48:49], v[58:59], 0, v[48:49]
	v_lshl_add_u64 v[50:51], v[58:59], 0, v[50:51]
	v_lshl_add_u64 v[60:61], v[58:59], 0, v[60:61]
	v_lshl_add_u64 v[56:57], v[58:59], 0, v[56:57]
	global_load_dwordx4 v[36:39], v[32:33], off
	s_nop 0
	global_load_dwordx4 v[32:35], v[34:35], off
	s_nop 0
	global_load_dwordx4 v[44:47], v[40:41], off
	s_nop 0
	global_load_dwordx4 v[40:43], v[42:43], off
	s_nop 0
	global_load_dwordx4 v[52:55], v[48:49], off
	s_nop 0
	global_load_dwordx4 v[48:51], v[50:51], off
	s_nop 0
	global_load_dwordx4 v[60:63], v[60:61], off
	s_nop 0
	global_load_dwordx4 v[56:59], v[56:57], off

.LBB0_125:
	v_add_u32_e32 v174, s51, v173
	v_cmp_gt_i32_e32 vcc, s46, v174
	s_and_saveexec_b64 s[34:35], vcc
	s_cbranch_execz .LBB0_127
	v_ashrrev_i32_e32 v32, 31, v174
	v_lshrrev_b32_e32 v32, 27, v32
	v_add_u32_e32 v32, v174, v32
	v_lshlrev_b32_e32 v33, 1, v32
	v_and_b32_e32 v32, 0x7ffffe0, v32
	v_sub_u32_e32 v32, v174, v32
	v_and_or_b32 v56, v33, s47, v159
	v_lshlrev_b32_e32 v32, 5, v32
	v_ashrrev_i32_e32 v33, 31, v32
	v_ashrrev_i32_e32 v57, 31, v56
	v_lshl_add_u64 v[58:59], v[32:33], 2, v[154:155]
	v_lshlrev_b64 v[32:33], 12, v[56:57]
	v_or_b32_e32 v34, 8, v56
	v_or_b32_e32 v40, 16, v56
	v_or_b32_e32 v42, 24, v56
	v_or_b32_e32 v48, 32, v56
	v_or_b32_e32 v50, 40, v56
	v_or_b32_e32 v60, 48, v56
	v_or_b32_e32 v56, 56, v56
	v_ashrrev_i32_e32 v35, 31, v34
	v_ashrrev_i32_e32 v41, 31, v40
	v_ashrrev_i32_e32 v43, 31, v42
	v_ashrrev_i32_e32 v49, 31, v48
	v_ashrrev_i32_e32 v51, 31, v50
	v_ashrrev_i32_e32 v61, 31, v60
	v_ashrrev_i32_e32 v57, 31, v56
	v_lshlrev_b64 v[34:35], 12, v[34:35]
	v_lshlrev_b64 v[40:41], 12, v[40:41]
	v_lshlrev_b64 v[42:43], 12, v[42:43]
	v_lshlrev_b64 v[48:49], 12, v[48:49]
	v_lshlrev_b64 v[50:51], 12, v[50:51]
	v_lshlrev_b64 v[60:61], 12, v[60:61]
	v_lshlrev_b64 v[56:57], 12, v[56:57]
	v_lshl_add_u64 v[32:33], v[58:59], 0, v[32:33]
	v_lshl_add_u64 v[34:35], v[58:59], 0, v[34:35]
	v_lshl_add_u64 v[40:41], v[58:59], 0, v[40:41]
	v_lshl_add_u64 v[42:43], v[58:59], 0, v[42:43]
	v_lshl_add_u64 v[48:49], v[58:59], 0, v[48:49]
	v_lshl_add_u64 v[50:51], v[58:59], 0, v[50:51]
	v_lshl_add_u64 v[60:61], v[58:59], 0, v[60:61]
	v_lshl_add_u64 v[56:57], v[58:59], 0, v[56:57]
	global_load_dwordx4 v[36:39], v[32:33], off
	s_nop 0
	global_load_dwordx4 v[32:35], v[34:35], off
	s_nop 0
	global_load_dwordx4 v[44:47], v[40:41], off
	s_nop 0
	global_load_dwordx4 v[40:43], v[42:43], off
	s_nop 0
	global_load_dwordx4 v[52:55], v[48:49], off
	s_nop 0
	global_load_dwordx4 v[48:51], v[50:51], off
	s_nop 0
	global_load_dwordx4 v[60:63], v[60:61], off
	s_nop 0
	global_load_dwordx4 v[56:59], v[56:57], off

.LBB0_139:
	v_add_u32_e32 v174, s41, v173
	v_cmp_gt_i32_e32 vcc, s49, v174
	s_and_saveexec_b64 s[34:35], vcc
	s_cbranch_execz .LBB0_141
	v_ashrrev_i32_e32 v32, 31, v174
	v_lshrrev_b32_e32 v32, 27, v32
	v_add_u32_e32 v32, v174, v32
	v_lshlrev_b32_e32 v33, 1, v32
	v_and_b32_e32 v32, 0x7ffffe0, v32
	v_sub_u32_e32 v32, v174, v32
	v_and_or_b32 v56, v33, s47, v159
	v_lshlrev_b32_e32 v32, 5, v32
	v_ashrrev_i32_e32 v33, 31, v32
	v_ashrrev_i32_e32 v57, 31, v56
	v_lshl_add_u64 v[58:59], v[32:33], 2, v[154:155]
	v_lshlrev_b64 v[32:33], 12, v[56:57]
	v_or_b32_e32 v34, 8, v56
	v_or_b32_e32 v40, 16, v56
	v_or_b32_e32 v42, 24, v56
	v_or_b32_e32 v48, 32, v56
	v_or_b32_e32 v50, 40, v56
	v_or_b32_e32 v60, 48, v56
	v_or_b32_e32 v56, 56, v56
	v_ashrrev_i32_e32 v35, 31, v34
	v_ashrrev_i32_e32 v41, 31, v40
	v_ashrrev_i32_e32 v43, 31, v42
	v_ashrrev_i32_e32 v49, 31, v48
	v_ashrrev_i32_e32 v51, 31, v50
	v_ashrrev_i32_e32 v61, 31, v60
	v_ashrrev_i32_e32 v57, 31, v56
	v_lshlrev_b64 v[34:35], 12, v[34:35]
	v_lshlrev_b64 v[40:41], 12, v[40:41]
	v_lshlrev_b64 v[42:43], 12, v[42:43]
	v_lshlrev_b64 v[48:49], 12, v[48:49]
	v_lshlrev_b64 v[50:51], 12, v[50:51]
	v_lshlrev_b64 v[60:61], 12, v[60:61]
	v_lshlrev_b64 v[56:57], 12, v[56:57]
	v_lshl_add_u64 v[32:33], v[58:59], 0, v[32:33]
	v_lshl_add_u64 v[34:35], v[58:59], 0, v[34:35]
	v_lshl_add_u64 v[40:41], v[58:59], 0, v[40:41]
	v_lshl_add_u64 v[42:43], v[58:59], 0, v[42:43]
	v_lshl_add_u64 v[48:49], v[58:59], 0, v[48:49]
	v_lshl_add_u64 v[50:51], v[58:59], 0, v[50:51]
	v_lshl_add_u64 v[60:61], v[58:59], 0, v[60:61]
	v_lshl_add_u64 v[56:57], v[58:59], 0, v[56:57]
	global_load_dwordx4 v[36:39], v[32:33], off
	s_nop 0
	global_load_dwordx4 v[32:35], v[34:35], off
	s_nop 0
	global_load_dwordx4 v[44:47], v[40:41], off
	s_nop 0
	global_load_dwordx4 v[40:43], v[42:43], off
	s_nop 0
	global_load_dwordx4 v[52:55], v[48:49], off
	s_nop 0
	global_load_dwordx4 v[48:51], v[50:51], off
	s_nop 0
	global_load_dwordx4 v[60:63], v[60:61], off
	s_nop 0
	global_load_dwordx4 v[56:59], v[56:57], off

.LBB0_151:
	v_add_u32_e32 v173, s41, v174
	v_cmp_gt_i32_e32 vcc, s49, v173
	s_and_saveexec_b64 s[28:29], vcc
	s_cbranch_execz .LBB0_153
	v_ashrrev_i32_e32 v32, 31, v173
	v_lshrrev_b32_e32 v32, 27, v32
	v_add_u32_e32 v32, v173, v32
	v_lshlrev_b32_e32 v33, 1, v32
	v_and_b32_e32 v32, 0x7ffffe0, v32
	v_sub_u32_e32 v32, v173, v32
	v_and_or_b32 v56, v33, s47, v159
	v_lshlrev_b32_e32 v32, 5, v32
	v_ashrrev_i32_e32 v33, 31, v32
	v_ashrrev_i32_e32 v57, 31, v56
	v_lshl_add_u64 v[58:59], v[32:33], 2, v[154:155]
	v_lshlrev_b64 v[32:33], 12, v[56:57]
	v_or_b32_e32 v34, 8, v56
	v_or_b32_e32 v40, 16, v56
	v_or_b32_e32 v42, 24, v56
	v_or_b32_e32 v48, 32, v56
	v_or_b32_e32 v50, 40, v56
	v_or_b32_e32 v60, 48, v56
	v_or_b32_e32 v56, 56, v56
	v_ashrrev_i32_e32 v35, 31, v34
	v_ashrrev_i32_e32 v41, 31, v40
	v_ashrrev_i32_e32 v43, 31, v42
	v_ashrrev_i32_e32 v49, 31, v48
	v_ashrrev_i32_e32 v51, 31, v50
	v_ashrrev_i32_e32 v61, 31, v60
	v_ashrrev_i32_e32 v57, 31, v56
	v_lshlrev_b64 v[34:35], 12, v[34:35]
	v_lshlrev_b64 v[40:41], 12, v[40:41]
	v_lshlrev_b64 v[42:43], 12, v[42:43]
	v_lshlrev_b64 v[48:49], 12, v[48:49]
	v_lshlrev_b64 v[50:51], 12, v[50:51]
	v_lshlrev_b64 v[60:61], 12, v[60:61]
	v_lshlrev_b64 v[56:57], 12, v[56:57]
	v_lshl_add_u64 v[32:33], v[58:59], 0, v[32:33]
	v_lshl_add_u64 v[34:35], v[58:59], 0, v[34:35]
	v_lshl_add_u64 v[40:41], v[58:59], 0, v[40:41]
	v_lshl_add_u64 v[42:43], v[58:59], 0, v[42:43]
	v_lshl_add_u64 v[48:49], v[58:59], 0, v[48:49]
	v_lshl_add_u64 v[50:51], v[58:59], 0, v[50:51]
	v_lshl_add_u64 v[60:61], v[58:59], 0, v[60:61]
	v_lshl_add_u64 v[56:57], v[58:59], 0, v[56:57]
	global_load_dwordx4 v[36:39], v[32:33], off
	s_nop 0
	global_load_dwordx4 v[32:35], v[34:35], off
	s_nop 0
	global_load_dwordx4 v[44:47], v[40:41], off
	s_nop 0
	global_load_dwordx4 v[40:43], v[42:43], off
	s_nop 0
	global_load_dwordx4 v[52:55], v[48:49], off
	s_nop 0
	global_load_dwordx4 v[48:51], v[50:51], off
	s_nop 0
	global_load_dwordx4 v[60:63], v[60:61], off
	s_nop 0
	global_load_dwordx4 v[56:59], v[56:57], off
